# v33: v31 + K-loop bookkeeping SALU (tail increments and next iteration's pointer selects) hoisted into the last MFMA segment of each iteration, all five GEMM loops
# speedup vs baseline: 1.0034x; 1.0034x over previous
.LBB0_230:
	s_add_u32 s98, s0, 0xfff00000
	s_addc_u32 s99, s1, -1
	s_add_u32 s28, s0, 0xfff00080
	s_addc_u32 s29, s1, -1
	s_add_i32 s51, 0, 0x10000
	s_cmp_eq_u32 s50, 60
	s_cselect_b32 s31, s34, s29
	s_cselect_b32 s30, s35, s28
	s_cselect_b32 s29, s27, s43
	s_cselect_b32 s28, s40, s41
	s_add_i32 s77, 0, 0x14000
.Lkb_230:
	v_add_u32_e32 v0, s51, v179
	ds_read_b128 v[130:133], v0
	ds_read_b128 v[134:137], v0 offset:1024
	ds_read_b128 v[138:141], v0 offset:2048
	ds_read_b128 v[142:145], v0 offset:3072
	v_add_u32_e32 v0, s77, v179
	ds_read_b128 v[146:149], v0
	ds_read_b128 v[150:153], v0 offset:1024
	ds_read_b128 v[154:157], v0 offset:2048
	ds_read_b128 v[158:161], v0 offset:3072
	s_mov_b32 m0, s54
	ds_read_b128 v[174:177], v192
	ds_read_b128 v[180:183], v192 offset:1024
	ds_read_b128 v[184:187], v192 offset:2048
	ds_read_b128 v[188:191], v192 offset:3072
	ds_read_b128 v[200:203], v192 offset:4096
	ds_read_b128 v[204:207], v192 offset:5120
	ds_read_b128 v[208:211], v192 offset:6144
	ds_read_b128 v[212:215], v192 offset:7168
	global_load_lds_dwordx4 v168, s[98:99]
	s_mov_b32 m0, s55
	s_nop 0
	global_load_lds_dwordx4 v164, s[98:99]
	s_add_i32 m0, s14, 0xc000
	s_nop 0
	global_load_lds_dwordx4 v170, s[0:1]
	s_add_i32 m0, s14, 0xe000
	s_nop 0
	global_load_lds_dwordx4 v172, s[0:1]
	s_waitcnt vmcnt(8)
	s_waitcnt lgkmcnt(0)
	s_barrier
	s_waitcnt lgkmcnt(0)
	v_mfma_f32_16x16x32_bf16 v[126:129], v[130:133], v[174:177], v[126:129]
	v_mfma_f32_16x16x32_bf16 v[126:129], v[134:137], v[180:183], v[126:129]
	v_mfma_f32_16x16x32_bf16 v[110:113], v[130:133], v[184:187], v[110:113]
	v_mfma_f32_16x16x32_bf16 v[110:113], v[134:137], v[188:191], v[110:113]
	v_mfma_f32_16x16x32_bf16 v[94:97], v[130:133], v[200:203], v[94:97]
	v_mfma_f32_16x16x32_bf16 v[94:97], v[134:137], v[204:207], v[94:97]
	v_mfma_f32_16x16x32_bf16 v[78:81], v[130:133], v[208:211], v[78:81]
	v_mfma_f32_16x16x32_bf16 v[78:81], v[134:137], v[212:215], v[78:81]
	v_mfma_f32_16x16x32_bf16 v[122:125], v[138:141], v[174:177], v[122:125]
	v_mfma_f32_16x16x32_bf16 v[122:125], v[142:145], v[180:183], v[122:125]
	v_mfma_f32_16x16x32_bf16 v[106:109], v[138:141], v[184:187], v[106:109]
	v_mfma_f32_16x16x32_bf16 v[106:109], v[142:145], v[188:191], v[106:109]
	v_mfma_f32_16x16x32_bf16 v[90:93], v[138:141], v[200:203], v[90:93]
	v_mfma_f32_16x16x32_bf16 v[90:93], v[142:145], v[204:207], v[90:93]
	v_mfma_f32_16x16x32_bf16 v[74:77], v[138:141], v[208:211], v[74:77]
	v_mfma_f32_16x16x32_bf16 v[74:77], v[142:145], v[212:215], v[74:77]
	v_mfma_f32_16x16x32_bf16 v[118:121], v[146:149], v[174:177], v[118:121]
	v_mfma_f32_16x16x32_bf16 v[118:121], v[150:153], v[180:183], v[118:121]
	v_mfma_f32_16x16x32_bf16 v[102:105], v[146:149], v[184:187], v[102:105]
	v_mfma_f32_16x16x32_bf16 v[102:105], v[150:153], v[188:191], v[102:105]
	v_mfma_f32_16x16x32_bf16 v[86:89], v[146:149], v[200:203], v[86:89]
	v_mfma_f32_16x16x32_bf16 v[86:89], v[150:153], v[204:207], v[86:89]
	v_mfma_f32_16x16x32_bf16 v[70:73], v[146:149], v[208:211], v[70:73]
	v_mfma_f32_16x16x32_bf16 v[70:73], v[150:153], v[212:215], v[70:73]
	v_mfma_f32_16x16x32_bf16 v[114:117], v[154:157], v[174:177], v[114:117]
	v_mfma_f32_16x16x32_bf16 v[114:117], v[158:161], v[180:183], v[114:117]
	v_mfma_f32_16x16x32_bf16 v[98:101], v[154:157], v[184:187], v[98:101]
	v_mfma_f32_16x16x32_bf16 v[98:101], v[158:161], v[188:191], v[98:101]
	v_mfma_f32_16x16x32_bf16 v[82:85], v[154:157], v[200:203], v[82:85]
	v_mfma_f32_16x16x32_bf16 v[82:85], v[158:161], v[204:207], v[82:85]
	v_mfma_f32_16x16x32_bf16 v[66:69], v[154:157], v[208:211], v[66:69]
	v_mfma_f32_16x16x32_bf16 v[66:69], v[158:161], v[212:215], v[66:69]
	s_barrier
	s_add_i32 s51, s51, s9
	s_mov_b32 m0, s51
	ds_read_b128 v[174:177], v192 offset:16384
	ds_read_b128 v[180:183], v192 offset:17408
	ds_read_b128 v[184:187], v192 offset:18432
	ds_read_b128 v[188:191], v192 offset:19456
	ds_read_b128 v[200:203], v192 offset:20480
	ds_read_b128 v[204:207], v192 offset:21504
	ds_read_b128 v[208:211], v192 offset:22528
	ds_read_b128 v[212:215], v192 offset:23552
	global_load_lds_dwordx4 v166, s[28:29]
	s_add_i32 m0, s51, 0x2000
	s_add_u32 s80, s28, 0x100000
	s_addc_u32 s81, s29, 0
	s_add_i32 s51, s77, s9
	global_load_lds_dwordx4 v162, s[28:29]
	s_mov_b32 m0, s51
	s_nop 0
	global_load_lds_dwordx4 v166, s[80:81]
	s_add_i32 m0, s51, 0x2000
	s_nop 0
	global_load_lds_dwordx4 v162, s[80:81]
	s_waitcnt vmcnt(6)
	s_waitcnt lgkmcnt(0)
	s_barrier
	s_waitcnt lgkmcnt(0)
	v_mfma_f32_16x16x32_bf16 v[62:65], v[130:133], v[174:177], v[62:65]
	v_mfma_f32_16x16x32_bf16 v[62:65], v[134:137], v[180:183], v[62:65]
	v_mfma_f32_16x16x32_bf16 v[46:49], v[130:133], v[184:187], v[46:49]
	v_mfma_f32_16x16x32_bf16 v[46:49], v[134:137], v[188:191], v[46:49]
	v_mfma_f32_16x16x32_bf16 v[30:33], v[130:133], v[200:203], v[30:33]
	v_mfma_f32_16x16x32_bf16 v[30:33], v[134:137], v[204:207], v[30:33]
	v_mfma_f32_16x16x32_bf16 v[14:17], v[130:133], v[208:211], v[14:17]
	v_mfma_f32_16x16x32_bf16 v[14:17], v[134:137], v[212:215], v[14:17]
	v_mfma_f32_16x16x32_bf16 v[58:61], v[138:141], v[174:177], v[58:61]
	v_mfma_f32_16x16x32_bf16 v[58:61], v[142:145], v[180:183], v[58:61]
	v_mfma_f32_16x16x32_bf16 v[42:45], v[138:141], v[184:187], v[42:45]
	v_mfma_f32_16x16x32_bf16 v[42:45], v[142:145], v[188:191], v[42:45]
	v_mfma_f32_16x16x32_bf16 v[26:29], v[138:141], v[200:203], v[26:29]
	v_mfma_f32_16x16x32_bf16 v[26:29], v[142:145], v[204:207], v[26:29]
	v_mfma_f32_16x16x32_bf16 v[10:13], v[138:141], v[208:211], v[10:13]
	v_mfma_f32_16x16x32_bf16 v[10:13], v[142:145], v[212:215], v[10:13]
	v_mfma_f32_16x16x32_bf16 v[54:57], v[146:149], v[174:177], v[54:57]
	v_mfma_f32_16x16x32_bf16 v[54:57], v[150:153], v[180:183], v[54:57]
	v_mfma_f32_16x16x32_bf16 v[38:41], v[146:149], v[184:187], v[38:41]
	v_mfma_f32_16x16x32_bf16 v[38:41], v[150:153], v[188:191], v[38:41]
	v_mfma_f32_16x16x32_bf16 v[22:25], v[146:149], v[200:203], v[22:25]
	v_mfma_f32_16x16x32_bf16 v[22:25], v[150:153], v[204:207], v[22:25]
	v_mfma_f32_16x16x32_bf16 v[6:9], v[146:149], v[208:211], v[6:9]
	v_mfma_f32_16x16x32_bf16 v[6:9], v[150:153], v[212:215], v[6:9]
	v_mfma_f32_16x16x32_bf16 v[50:53], v[154:157], v[174:177], v[50:53]
	v_mfma_f32_16x16x32_bf16 v[50:53], v[158:161], v[180:183], v[50:53]
	v_mfma_f32_16x16x32_bf16 v[34:37], v[154:157], v[184:187], v[34:37]
	v_mfma_f32_16x16x32_bf16 v[34:37], v[158:161], v[188:191], v[34:37]
	v_mfma_f32_16x16x32_bf16 v[18:21], v[154:157], v[200:203], v[18:21]
	v_mfma_f32_16x16x32_bf16 v[18:21], v[158:161], v[204:207], v[18:21]
	v_mfma_f32_16x16x32_bf16 v[2:5], v[154:157], v[208:211], v[2:5]
	v_mfma_f32_16x16x32_bf16 v[2:5], v[158:161], v[212:215], v[2:5]
	s_barrier
	s_add_i32 s51, 0, 0x18000
	v_add_u32_e32 v0, s51, v179
	s_add_i32 s77, 0, 0x1c000
	ds_read_b128 v[130:133], v0
	ds_read_b128 v[134:137], v0 offset:1024
	ds_read_b128 v[138:141], v0 offset:2048
	ds_read_b128 v[142:145], v0 offset:3072
	v_add_u32_e32 v0, s77, v179
	ds_read_b128 v[146:149], v0
	ds_read_b128 v[150:153], v0 offset:1024
	ds_read_b128 v[154:157], v0 offset:2048
	ds_read_b128 v[158:161], v0 offset:3072
	s_mov_b32 m0, s14
	ds_read_b128 v[174:177], v192 offset:32768
	ds_read_b128 v[180:183], v192 offset:33792
	ds_read_b128 v[184:187], v192 offset:34816
	ds_read_b128 v[188:191], v192 offset:35840
	ds_read_b128 v[200:203], v192 offset:36864
	ds_read_b128 v[204:207], v192 offset:37888
	ds_read_b128 v[208:211], v192 offset:38912
	ds_read_b128 v[212:215], v192 offset:39936
	global_load_lds_dwordx4 v168, s[30:31]
	s_mov_b32 m0, s15
	s_nop 0
	global_load_lds_dwordx4 v164, s[30:31]
	s_add_u32 s30, s30, 0x100000
	s_addc_u32 s31, s31, 0
	s_mov_b32 m0, s52
	s_nop 0
	global_load_lds_dwordx4 v168, s[30:31]
	s_mov_b32 m0, s53
	s_nop 0
	global_load_lds_dwordx4 v164, s[30:31]
	s_waitcnt vmcnt(8)
	s_waitcnt lgkmcnt(0)
	s_barrier
	s_waitcnt lgkmcnt(0)
	v_mfma_f32_16x16x32_bf16 v[126:129], v[130:133], v[174:177], v[126:129]
	v_mfma_f32_16x16x32_bf16 v[126:129], v[134:137], v[180:183], v[126:129]
	v_mfma_f32_16x16x32_bf16 v[110:113], v[130:133], v[184:187], v[110:113]
	v_mfma_f32_16x16x32_bf16 v[110:113], v[134:137], v[188:191], v[110:113]
	v_mfma_f32_16x16x32_bf16 v[94:97], v[130:133], v[200:203], v[94:97]
	v_mfma_f32_16x16x32_bf16 v[94:97], v[134:137], v[204:207], v[94:97]
	v_mfma_f32_16x16x32_bf16 v[78:81], v[130:133], v[208:211], v[78:81]
	v_mfma_f32_16x16x32_bf16 v[78:81], v[134:137], v[212:215], v[78:81]
	v_mfma_f32_16x16x32_bf16 v[122:125], v[138:141], v[174:177], v[122:125]
	v_mfma_f32_16x16x32_bf16 v[122:125], v[142:145], v[180:183], v[122:125]
	v_mfma_f32_16x16x32_bf16 v[106:109], v[138:141], v[184:187], v[106:109]
	v_mfma_f32_16x16x32_bf16 v[106:109], v[142:145], v[188:191], v[106:109]
	v_mfma_f32_16x16x32_bf16 v[90:93], v[138:141], v[200:203], v[90:93]
	v_mfma_f32_16x16x32_bf16 v[90:93], v[142:145], v[204:207], v[90:93]
	v_mfma_f32_16x16x32_bf16 v[74:77], v[138:141], v[208:211], v[74:77]
	v_mfma_f32_16x16x32_bf16 v[74:77], v[142:145], v[212:215], v[74:77]
	v_mfma_f32_16x16x32_bf16 v[118:121], v[146:149], v[174:177], v[118:121]
	v_mfma_f32_16x16x32_bf16 v[118:121], v[150:153], v[180:183], v[118:121]
	v_mfma_f32_16x16x32_bf16 v[102:105], v[146:149], v[184:187], v[102:105]
	v_mfma_f32_16x16x32_bf16 v[102:105], v[150:153], v[188:191], v[102:105]
	v_mfma_f32_16x16x32_bf16 v[86:89], v[146:149], v[200:203], v[86:89]
	v_mfma_f32_16x16x32_bf16 v[86:89], v[150:153], v[204:207], v[86:89]
	v_mfma_f32_16x16x32_bf16 v[70:73], v[146:149], v[208:211], v[70:73]
	v_mfma_f32_16x16x32_bf16 v[70:73], v[150:153], v[212:215], v[70:73]
	v_mfma_f32_16x16x32_bf16 v[114:117], v[154:157], v[174:177], v[114:117]
	v_mfma_f32_16x16x32_bf16 v[114:117], v[158:161], v[180:183], v[114:117]
	v_mfma_f32_16x16x32_bf16 v[98:101], v[154:157], v[184:187], v[98:101]
	v_mfma_f32_16x16x32_bf16 v[98:101], v[158:161], v[188:191], v[98:101]
	v_mfma_f32_16x16x32_bf16 v[82:85], v[154:157], v[200:203], v[82:85]
	v_mfma_f32_16x16x32_bf16 v[82:85], v[158:161], v[204:207], v[82:85]
	v_mfma_f32_16x16x32_bf16 v[66:69], v[154:157], v[208:211], v[66:69]
	v_mfma_f32_16x16x32_bf16 v[66:69], v[158:161], v[212:215], v[66:69]
	s_barrier
	s_add_u32 s98, s28, 0x80
	s_addc_u32 s99, s29, 0
	s_add_i32 s30, s51, s9
	s_mov_b32 m0, s30
	ds_read_b128 v[174:177], v192 offset:49152
	ds_read_b128 v[180:183], v192 offset:50176
	ds_read_b128 v[184:187], v192 offset:51200
	ds_read_b128 v[188:191], v192 offset:52224
	ds_read_b128 v[200:203], v192 offset:53248
	ds_read_b128 v[204:207], v192 offset:54272
	ds_read_b128 v[208:211], v192 offset:55296
	ds_read_b128 v[212:215], v192 offset:56320
	global_load_lds_dwordx4 v166, s[98:99]
	s_add_i32 m0, s30, 0x2000
	s_add_u32 s28, s28, 0x100080
	s_addc_u32 s29, s29, 0
	s_add_i32 s30, s77, s9
	global_load_lds_dwordx4 v162, s[98:99]
	s_mov_b32 m0, s30
	s_nop 0
	global_load_lds_dwordx4 v166, s[28:29]
	s_add_i32 m0, s30, 0x2000
	s_nop 0
	global_load_lds_dwordx4 v162, s[28:29]
	s_waitcnt vmcnt(6)
	s_waitcnt lgkmcnt(0)
	s_barrier
	s_waitcnt lgkmcnt(0)
	v_mfma_f32_16x16x32_bf16 v[62:65], v[130:133], v[174:177], v[62:65]
	v_mfma_f32_16x16x32_bf16 v[62:65], v[134:137], v[180:183], v[62:65]
	v_mfma_f32_16x16x32_bf16 v[46:49], v[130:133], v[184:187], v[46:49]
	v_mfma_f32_16x16x32_bf16 v[46:49], v[134:137], v[188:191], v[46:49]
	v_mfma_f32_16x16x32_bf16 v[30:33], v[130:133], v[200:203], v[30:33]
	v_mfma_f32_16x16x32_bf16 v[30:33], v[134:137], v[204:207], v[30:33]
	v_mfma_f32_16x16x32_bf16 v[14:17], v[130:133], v[208:211], v[14:17]
	v_mfma_f32_16x16x32_bf16 v[14:17], v[134:137], v[212:215], v[14:17]
	v_mfma_f32_16x16x32_bf16 v[58:61], v[138:141], v[174:177], v[58:61]
	v_mfma_f32_16x16x32_bf16 v[58:61], v[142:145], v[180:183], v[58:61]
	v_mfma_f32_16x16x32_bf16 v[42:45], v[138:141], v[184:187], v[42:45]
	v_mfma_f32_16x16x32_bf16 v[42:45], v[142:145], v[188:191], v[42:45]
	s_add_i32 s50, s50, 2
	v_mfma_f32_16x16x32_bf16 v[26:29], v[138:141], v[200:203], v[26:29]
	v_mfma_f32_16x16x32_bf16 v[26:29], v[142:145], v[204:207], v[26:29]
	s_add_u32 s0, s0, 0x100
	s_addc_u32 s1, s1, 0
	v_mfma_f32_16x16x32_bf16 v[10:13], v[138:141], v[208:211], v[10:13]
	v_mfma_f32_16x16x32_bf16 v[10:13], v[142:145], v[212:215], v[10:13]
	s_add_u32 s41, s41, 0x100
	s_addc_u32 s43, s43, 0
	v_mfma_f32_16x16x32_bf16 v[54:57], v[146:149], v[174:177], v[54:57]
	v_mfma_f32_16x16x32_bf16 v[54:57], v[150:153], v[180:183], v[54:57]
	s_add_u32 s98, s0, 0xfff00000
	s_addc_u32 s99, s1, -1
	v_mfma_f32_16x16x32_bf16 v[38:41], v[146:149], v[184:187], v[38:41]
	v_mfma_f32_16x16x32_bf16 v[38:41], v[150:153], v[188:191], v[38:41]
	s_add_u32 s28, s0, 0xfff00080
	s_addc_u32 s29, s1, -1
	v_mfma_f32_16x16x32_bf16 v[22:25], v[146:149], v[200:203], v[22:25]
	v_mfma_f32_16x16x32_bf16 v[22:25], v[150:153], v[204:207], v[22:25]
	s_add_i32 s51, 0, 0x10000
	v_mfma_f32_16x16x32_bf16 v[6:9], v[146:149], v[208:211], v[6:9]
	v_mfma_f32_16x16x32_bf16 v[6:9], v[150:153], v[212:215], v[6:9]
	s_cmp_eq_u32 s50, 60
	s_cselect_b32 s31, s34, s29
	s_cselect_b32 s30, s35, s28
	s_cselect_b32 s29, s27, s43
	s_cselect_b32 s28, s40, s41
	v_mfma_f32_16x16x32_bf16 v[50:53], v[154:157], v[174:177], v[50:53]
	v_mfma_f32_16x16x32_bf16 v[50:53], v[158:161], v[180:183], v[50:53]
	s_add_i32 s77, 0, 0x14000
	v_mfma_f32_16x16x32_bf16 v[34:37], v[154:157], v[184:187], v[34:37]
	v_mfma_f32_16x16x32_bf16 v[34:37], v[158:161], v[188:191], v[34:37]
	s_cmp_gt_u32 s50, 61
	v_mfma_f32_16x16x32_bf16 v[18:21], v[154:157], v[200:203], v[18:21]
	v_mfma_f32_16x16x32_bf16 v[18:21], v[158:161], v[204:207], v[18:21]
	v_mfma_f32_16x16x32_bf16 v[2:5], v[154:157], v[208:211], v[2:5]
	v_mfma_f32_16x16x32_bf16 v[2:5], v[158:161], v[212:215], v[2:5]
	s_barrier
	s_cbranch_scc0 .Lkb_230
	s_and_b64 vcc, exec, s[22:23]
	s_cbranch_vccz .LBB0_233
	s_barrier

.LBB0_300:
	s_add_u32 s100, s0, 0xfff80000
	s_addc_u32 s101, s1, -1
	s_add_u32 s28, s0, 0xfff80080
	s_addc_u32 s29, s1, -1
	s_add_i32 s42, 0, 0x10000
	s_cmp_eq_u32 s41, 28
	s_cselect_b32 s31, s18, s29
	s_cselect_b32 s30, s19, s28
	s_cselect_b32 s29, s27, s40
	s_cselect_b32 s28, s34, s35
	s_add_i32 s49, 0, 0x14000
.Lkb_300:
	v_add_u32_e32 v0, s42, v199
	ds_read_b128 v[2:5], v0
	ds_read_b128 v[6:9], v0 offset:1024
	ds_read_b128 v[10:13], v0 offset:2048
	ds_read_b128 v[14:17], v0 offset:3072
	v_add_u32_e32 v0, s49, v199
	ds_read_b128 v[146:149], v0
	ds_read_b128 v[150:153], v0 offset:1024
	ds_read_b128 v[154:157], v0 offset:2048
	ds_read_b128 v[158:161], v0 offset:3072
	s_mov_b32 m0, s15
	ds_read_b128 v[174:177], v250
	ds_read_b128 v[178:181], v250 offset:1024
	ds_read_b128 v[182:185], v250 offset:2048
	ds_read_b128 v[186:189], v250 offset:3072
	ds_read_b128 v[190:193], v250 offset:4096
	ds_read_b128 v[200:203], v250 offset:5120
	ds_read_b128 v[204:207], v250 offset:6144
	ds_read_b128 v[208:211], v250 offset:7168
	global_load_lds_dwordx4 v162, s[100:101]
	s_mov_b32 m0, s88
	s_nop 0
	global_load_lds_dwordx4 v166, s[100:101]
	s_add_i32 m0, s21, 0xc000
	s_nop 0
	global_load_lds_dwordx4 v170, s[0:1]
	s_add_i32 m0, s21, 0xe000
	s_nop 0
	global_load_lds_dwordx4 v172, s[0:1]
	s_cmp_eq_u32 s41, 28
	s_cbranch_scc1 .Lspf_w0
	s_waitcnt vmcnt(8)
	s_branch .Lspf_j0

.Lspf_j2:
	s_waitcnt lgkmcnt(0)
	s_barrier
	s_waitcnt lgkmcnt(0)
	v_mfma_i32_16x16x64_i8 v[142:145], v[34:37], v[174:177], v[142:145]
	v_mfma_i32_16x16x64_i8 v[142:145], v[38:41], v[178:181], v[142:145]
	v_mfma_i32_16x16x64_i8 v[134:137], v[34:37], v[182:185], v[134:137]
	v_mfma_i32_16x16x64_i8 v[134:137], v[38:41], v[186:189], v[134:137]
	v_mfma_i32_16x16x64_i8 v[122:125], v[34:37], v[190:193], v[122:125]
	v_mfma_i32_16x16x64_i8 v[122:125], v[38:41], v[200:203], v[122:125]
	v_mfma_i32_16x16x64_i8 v[106:109], v[34:37], v[204:207], v[106:109]
	v_mfma_i32_16x16x64_i8 v[106:109], v[38:41], v[208:211], v[106:109]
	v_mfma_i32_16x16x64_i8 v[138:141], v[58:61], v[174:177], v[138:141]
	v_mfma_i32_16x16x64_i8 v[138:141], v[62:65], v[178:181], v[138:141]
	v_mfma_i32_16x16x64_i8 v[130:133], v[58:61], v[182:185], v[130:133]
	v_mfma_i32_16x16x64_i8 v[130:133], v[62:65], v[186:189], v[130:133]
	v_mfma_i32_16x16x64_i8 v[114:117], v[58:61], v[190:193], v[114:117]
	v_mfma_i32_16x16x64_i8 v[114:117], v[62:65], v[200:203], v[114:117]
	v_mfma_i32_16x16x64_i8 v[98:101], v[58:61], v[204:207], v[98:101]
	v_mfma_i32_16x16x64_i8 v[98:101], v[62:65], v[208:211], v[98:101]
	v_mfma_i32_16x16x64_i8 v[126:129], v[146:149], v[174:177], v[126:129]
	v_mfma_i32_16x16x64_i8 v[126:129], v[150:153], v[178:181], v[126:129]
	v_mfma_i32_16x16x64_i8 v[110:113], v[146:149], v[182:185], v[110:113]
	v_mfma_i32_16x16x64_i8 v[110:113], v[150:153], v[186:189], v[110:113]
	v_mfma_i32_16x16x64_i8 v[94:97], v[146:149], v[190:193], v[94:97]
	v_mfma_i32_16x16x64_i8 v[94:97], v[150:153], v[200:203], v[94:97]
	v_mfma_i32_16x16x64_i8 v[86:89], v[146:149], v[204:207], v[86:89]
	v_mfma_i32_16x16x64_i8 v[86:89], v[150:153], v[208:211], v[86:89]
	v_mfma_i32_16x16x64_i8 v[118:121], v[154:157], v[174:177], v[118:121]
	v_mfma_i32_16x16x64_i8 v[118:121], v[158:161], v[178:181], v[118:121]
	v_mfma_i32_16x16x64_i8 v[102:105], v[154:157], v[182:185], v[102:105]
	v_mfma_i32_16x16x64_i8 v[102:105], v[158:161], v[186:189], v[102:105]
	v_mfma_i32_16x16x64_i8 v[90:93], v[154:157], v[190:193], v[90:93]
	v_mfma_i32_16x16x64_i8 v[90:93], v[158:161], v[200:203], v[90:93]
	v_mfma_i32_16x16x64_i8 v[82:85], v[154:157], v[204:207], v[82:85]
	v_mfma_i32_16x16x64_i8 v[82:85], v[158:161], v[208:211], v[82:85]
	s_barrier
	s_add_i32 s30, s42, s81
	s_add_u32 s98, s28, 0x80
	s_addc_u32 s99, s29, 0
	s_mov_b32 m0, s30
	ds_read_b128 v[174:177], v250 offset:49152
	ds_read_b128 v[178:181], v250 offset:50176
	ds_read_b128 v[182:185], v250 offset:51200
	ds_read_b128 v[186:189], v250 offset:52224
	ds_read_b128 v[190:193], v250 offset:53248
	ds_read_b128 v[200:203], v250 offset:54272
	ds_read_b128 v[204:207], v250 offset:55296
	ds_read_b128 v[208:211], v250 offset:56320
	global_load_lds_dwordx4 v164, s[98:99]
	s_add_i32 m0, s30, 0x2000
	s_add_u32 s28, s28, 0x80080
	s_addc_u32 s29, s29, 0
	s_add_i32 s30, s43, s81
	global_load_lds_dwordx4 v168, s[98:99]
	s_mov_b32 m0, s30
	s_nop 0
	global_load_lds_dwordx4 v164, s[28:29]
	s_add_i32 m0, s30, 0x2000
	s_nop 0
	global_load_lds_dwordx4 v168, s[28:29]
	s_waitcnt vmcnt(6)
	s_waitcnt lgkmcnt(0)
	s_barrier
	s_waitcnt lgkmcnt(0)
	v_mfma_i32_16x16x64_i8 v[78:81], v[34:37], v[174:177], v[78:81]
	v_mfma_i32_16x16x64_i8 v[78:81], v[38:41], v[178:181], v[78:81]
	v_mfma_i32_16x16x64_i8 v[70:73], v[34:37], v[182:185], v[70:73]
	v_mfma_i32_16x16x64_i8 v[70:73], v[38:41], v[186:189], v[70:73]
	v_mfma_i32_16x16x64_i8 v[54:57], v[34:37], v[190:193], v[54:57]
	v_mfma_i32_16x16x64_i8 v[54:57], v[38:41], v[200:203], v[54:57]
	v_mfma_i32_16x16x64_i8 v[2:5], v[34:37], v[204:207], v[2:5]
	v_mfma_i32_16x16x64_i8 v[38:41], v[38:41], v[208:211], v[2:5]
	v_mfma_i32_16x16x64_i8 v[74:77], v[58:61], v[174:177], v[74:77]
	v_mfma_i32_16x16x64_i8 v[74:77], v[62:65], v[178:181], v[74:77]
	v_mfma_i32_16x16x64_i8 v[66:69], v[58:61], v[182:185], v[66:69]
	v_mfma_i32_16x16x64_i8 v[66:69], v[62:65], v[186:189], v[66:69]
	s_add_i32 s41, s41, 2
	v_mfma_i32_16x16x64_i8 v[50:53], v[58:61], v[190:193], v[50:53]
	v_mfma_i32_16x16x64_i8 v[50:53], v[62:65], v[200:203], v[50:53]
	s_add_u32 s0, s0, 0x100
	s_addc_u32 s1, s1, 0
	v_mfma_i32_16x16x64_i8 v[2:5], v[58:61], v[204:207], v[6:9]
	v_mfma_i32_16x16x64_i8 v[34:37], v[62:65], v[208:211], v[2:5]
	s_add_u32 s35, s35, 0x100
	s_addc_u32 s40, s40, 0
	v_mfma_i32_16x16x64_i8 v[2:5], v[146:149], v[174:177], v[10:13]
	v_mfma_i32_16x16x64_i8 v[62:65], v[150:153], v[178:181], v[2:5]
	s_add_u32 s100, s0, 0xfff80000
	s_addc_u32 s101, s1, -1
	v_mfma_i32_16x16x64_i8 v[2:5], v[154:157], v[174:177], v[14:17]
	v_mfma_i32_16x16x64_i8 v[58:61], v[158:161], v[178:181], v[2:5]
	s_add_u32 s28, s0, 0xfff80080
	s_addc_u32 s29, s1, -1
	v_mfma_i32_16x16x64_i8 v[2:5], v[146:149], v[182:185], v[46:49]
	v_mfma_i32_16x16x64_i8 v[46:49], v[150:153], v[186:189], v[2:5]
	s_add_i32 s42, 0, 0x10000
	v_mfma_i32_16x16x64_i8 v[2:5], v[154:157], v[182:185], v[42:45]
	v_mfma_i32_16x16x64_i8 v[42:45], v[158:161], v[186:189], v[2:5]
	s_cmp_eq_u32 s41, 28
	s_cselect_b32 s31, s18, s29
	s_cselect_b32 s30, s19, s28
	s_cselect_b32 s29, s27, s40
	s_cselect_b32 s28, s34, s35
	v_mfma_i32_16x16x64_i8 v[2:5], v[146:149], v[190:193], v[30:33]
	v_mfma_i32_16x16x64_i8 v[30:33], v[150:153], v[200:203], v[2:5]
	s_add_i32 s49, 0, 0x14000
	v_mfma_i32_16x16x64_i8 v[2:5], v[154:157], v[190:193], v[26:29]
	v_mfma_i32_16x16x64_i8 v[26:29], v[158:161], v[200:203], v[2:5]
	s_cmp_gt_u32 s41, 29
	v_mfma_i32_16x16x64_i8 v[2:5], v[146:149], v[204:207], v[22:25]
	v_mfma_i32_16x16x64_i8 v[22:25], v[150:153], v[208:211], v[2:5]
	v_mfma_i32_16x16x64_i8 v[2:5], v[154:157], v[204:207], v[18:21]
	v_mfma_i32_16x16x64_i8 v[18:21], v[158:161], v[208:211], v[2:5]
	s_barrier
	s_cbranch_scc0 .Lkb_300
	s_and_b64 vcc, exec, s[52:53]
	s_cbranch_vccz .LBB0_303
	s_barrier

.LBB0_577:
	s_add_u32 s98, s30, 0xfff80000
	s_addc_u32 s99, s31, -1
	s_add_u32 s34, s30, 0xfff80080
	s_addc_u32 s35, s31, -1
	s_add_i32 s66, 0, 0x10000
	s_cmp_eq_u32 s57, 28
	s_cselect_b32 s43, s19, s35
	s_cselect_b32 s42, s23, s34
	s_cselect_b32 s35, s25, s56
	s_cselect_b32 s34, s54, s55
	s_add_i32 s73, 0, 0x14000
.Lkb_577:
	v_add_u32_e32 v0, s66, v228
	ds_read_b128 v[132:135], v0
	ds_read_b128 v[136:139], v0 offset:1024
	ds_read_b128 v[140:143], v0 offset:2048
	ds_read_b128 v[144:147], v0 offset:3072
	v_add_u32_e32 v0, s73, v228
	ds_read_b128 v[148:151], v0
	ds_read_b128 v[152:155], v0 offset:1024
	ds_read_b128 v[156:159], v0 offset:2048
	ds_read_b128 v[160:163], v0 offset:3072
	s_mov_b32 m0, s50
	ds_read_b128 v[164:167], v230
	ds_read_b128 v[168:171], v230 offset:1024
	ds_read_b128 v[172:175], v230 offset:2048
	ds_read_b128 v[176:179], v230 offset:3072
	ds_read_b128 v[180:183], v230 offset:4096
	ds_read_b128 v[184:187], v230 offset:5120
	ds_read_b128 v[188:191], v230 offset:6144
	ds_read_b128 v[192:195], v230 offset:7168
	global_load_lds_dwordx4 v206, s[98:99]
	s_mov_b32 m0, s51
	s_nop 0
	global_load_lds_dwordx4 v202, s[98:99]
	s_add_i32 m0, s46, 0xc000
	s_nop 0
	global_load_lds_dwordx4 v208, s[30:31]
	s_add_i32 m0, s46, 0xe000
	s_nop 0
	global_load_lds_dwordx4 v210, s[30:31]
	s_waitcnt vmcnt(8)
	s_waitcnt lgkmcnt(0)
	s_barrier
	s_waitcnt lgkmcnt(0)
	v_mfma_f32_16x16x32_bf16 v[128:131], v[132:135], v[164:167], v[128:131]
	v_mfma_f32_16x16x32_bf16 v[128:131], v[136:139], v[168:171], v[128:131]
	v_mfma_f32_16x16x32_bf16 v[120:123], v[132:135], v[172:175], v[120:123]
	v_mfma_f32_16x16x32_bf16 v[120:123], v[136:139], v[176:179], v[120:123]
	v_mfma_f32_16x16x32_bf16 v[112:115], v[132:135], v[180:183], v[112:115]
	v_mfma_f32_16x16x32_bf16 v[112:115], v[136:139], v[184:187], v[112:115]
	v_mfma_f32_16x16x32_bf16 v[104:107], v[132:135], v[188:191], v[104:107]
	v_mfma_f32_16x16x32_bf16 v[104:107], v[136:139], v[192:195], v[104:107]
	v_mfma_f32_16x16x32_bf16 v[124:127], v[140:143], v[164:167], v[124:127]
	v_mfma_f32_16x16x32_bf16 v[124:127], v[144:147], v[168:171], v[124:127]
	v_mfma_f32_16x16x32_bf16 v[116:119], v[140:143], v[172:175], v[116:119]
	v_mfma_f32_16x16x32_bf16 v[116:119], v[144:147], v[176:179], v[116:119]
	v_mfma_f32_16x16x32_bf16 v[108:111], v[140:143], v[180:183], v[108:111]
	v_mfma_f32_16x16x32_bf16 v[108:111], v[144:147], v[184:187], v[108:111]
	v_mfma_f32_16x16x32_bf16 v[100:103], v[140:143], v[188:191], v[100:103]
	v_mfma_f32_16x16x32_bf16 v[100:103], v[144:147], v[192:195], v[100:103]
	v_mfma_f32_16x16x32_bf16 v[96:99], v[148:151], v[164:167], v[96:99]
	v_mfma_f32_16x16x32_bf16 v[96:99], v[152:155], v[168:171], v[96:99]
	v_mfma_f32_16x16x32_bf16 v[88:91], v[148:151], v[172:175], v[88:91]
	v_mfma_f32_16x16x32_bf16 v[88:91], v[152:155], v[176:179], v[88:91]
	v_mfma_f32_16x16x32_bf16 v[80:83], v[148:151], v[180:183], v[80:83]
	v_mfma_f32_16x16x32_bf16 v[80:83], v[152:155], v[184:187], v[80:83]
	v_mfma_f32_16x16x32_bf16 v[72:75], v[148:151], v[188:191], v[72:75]
	v_mfma_f32_16x16x32_bf16 v[72:75], v[152:155], v[192:195], v[72:75]
	v_mfma_f32_16x16x32_bf16 v[92:95], v[156:159], v[164:167], v[92:95]
	v_mfma_f32_16x16x32_bf16 v[92:95], v[160:163], v[168:171], v[92:95]
	v_mfma_f32_16x16x32_bf16 v[84:87], v[156:159], v[172:175], v[84:87]
	v_mfma_f32_16x16x32_bf16 v[84:87], v[160:163], v[176:179], v[84:87]
	v_mfma_f32_16x16x32_bf16 v[76:79], v[156:159], v[180:183], v[76:79]
	v_mfma_f32_16x16x32_bf16 v[76:79], v[160:163], v[184:187], v[76:79]
	v_mfma_f32_16x16x32_bf16 v[68:71], v[156:159], v[188:191], v[68:71]
	v_mfma_f32_16x16x32_bf16 v[68:71], v[160:163], v[192:195], v[68:71]
	s_barrier
	s_add_i32 s66, s66, s15
	s_mov_b32 m0, s66
	ds_read_b128 v[164:167], v230 offset:16384
	ds_read_b128 v[168:171], v230 offset:17408
	ds_read_b128 v[172:175], v230 offset:18432
	ds_read_b128 v[176:179], v230 offset:19456
	ds_read_b128 v[180:183], v230 offset:20480
	ds_read_b128 v[184:187], v230 offset:21504
	ds_read_b128 v[188:191], v230 offset:22528
	ds_read_b128 v[192:195], v230 offset:23552
	global_load_lds_dwordx4 v204, s[34:35]
	s_add_i32 m0, s66, 0x2000
	s_add_u32 s66, s34, 0x80000
	s_addc_u32 s67, s35, 0
	s_add_i32 s73, s73, s15
	global_load_lds_dwordx4 v200, s[34:35]
	s_mov_b32 m0, s73
	s_nop 0
	global_load_lds_dwordx4 v204, s[66:67]
	s_add_i32 m0, s73, 0x2000
	s_nop 0
	global_load_lds_dwordx4 v200, s[66:67]
	s_waitcnt vmcnt(6)
	s_waitcnt lgkmcnt(0)
	s_barrier
	s_waitcnt lgkmcnt(0)
	v_mfma_f32_16x16x32_bf16 v[64:67], v[132:135], v[164:167], v[64:67]
	v_mfma_f32_16x16x32_bf16 v[64:67], v[136:139], v[168:171], v[64:67]
	v_mfma_f32_16x16x32_bf16 v[56:59], v[132:135], v[172:175], v[56:59]
	v_mfma_f32_16x16x32_bf16 v[56:59], v[136:139], v[176:179], v[56:59]
	v_mfma_f32_16x16x32_bf16 v[48:51], v[132:135], v[180:183], v[48:51]
	v_mfma_f32_16x16x32_bf16 v[48:51], v[136:139], v[184:187], v[48:51]
	v_mfma_f32_16x16x32_bf16 v[40:43], v[132:135], v[188:191], v[40:43]
	v_mfma_f32_16x16x32_bf16 v[40:43], v[136:139], v[192:195], v[40:43]
	v_mfma_f32_16x16x32_bf16 v[60:63], v[140:143], v[164:167], v[60:63]
	v_mfma_f32_16x16x32_bf16 v[60:63], v[144:147], v[168:171], v[60:63]
	v_mfma_f32_16x16x32_bf16 v[52:55], v[140:143], v[172:175], v[52:55]
	v_mfma_f32_16x16x32_bf16 v[52:55], v[144:147], v[176:179], v[52:55]
	v_mfma_f32_16x16x32_bf16 v[44:47], v[140:143], v[180:183], v[44:47]
	v_mfma_f32_16x16x32_bf16 v[44:47], v[144:147], v[184:187], v[44:47]
	v_mfma_f32_16x16x32_bf16 v[36:39], v[140:143], v[188:191], v[36:39]
	v_mfma_f32_16x16x32_bf16 v[36:39], v[144:147], v[192:195], v[36:39]
	v_mfma_f32_16x16x32_bf16 v[32:35], v[148:151], v[164:167], v[32:35]
	v_mfma_f32_16x16x32_bf16 v[32:35], v[152:155], v[168:171], v[32:35]
	v_mfma_f32_16x16x32_bf16 v[28:31], v[156:159], v[164:167], v[28:31]
	v_mfma_f32_16x16x32_bf16 v[28:31], v[160:163], v[168:171], v[28:31]
	v_mfma_f32_16x16x32_bf16 v[24:27], v[148:151], v[172:175], v[24:27]
	v_mfma_f32_16x16x32_bf16 v[24:27], v[152:155], v[176:179], v[24:27]
	v_mfma_f32_16x16x32_bf16 v[20:23], v[156:159], v[172:175], v[20:23]
	v_mfma_f32_16x16x32_bf16 v[20:23], v[160:163], v[176:179], v[20:23]
	v_mfma_f32_16x16x32_bf16 v[16:19], v[148:151], v[180:183], v[16:19]
	v_mfma_f32_16x16x32_bf16 v[16:19], v[152:155], v[184:187], v[16:19]
	v_mfma_f32_16x16x32_bf16 v[12:15], v[156:159], v[180:183], v[12:15]
	v_mfma_f32_16x16x32_bf16 v[12:15], v[160:163], v[184:187], v[12:15]
	v_mfma_f32_16x16x32_bf16 v[8:11], v[148:151], v[188:191], v[8:11]
	v_mfma_f32_16x16x32_bf16 v[8:11], v[152:155], v[192:195], v[8:11]
	v_mfma_f32_16x16x32_bf16 v[2:5], v[156:159], v[188:191], v[4:7]
	v_mfma_f32_16x16x32_bf16 v[2:5], v[160:163], v[192:195], v[2:5]
	s_barrier
	s_add_i32 s66, 0, 0x18000
	v_add_u32_e32 v0, s66, v228
	s_add_i32 s67, 0, 0x1c000
	ds_read_b128 v[132:135], v0
	ds_read_b128 v[136:139], v0 offset:1024
	ds_read_b128 v[140:143], v0 offset:2048
	ds_read_b128 v[144:147], v0 offset:3072
	v_add_u32_e32 v0, s67, v228
	ds_read_b128 v[148:151], v0
	ds_read_b128 v[152:155], v0 offset:1024
	ds_read_b128 v[156:159], v0 offset:2048
	ds_read_b128 v[160:163], v0 offset:3072
	s_mov_b32 m0, s46
	ds_read_b128 v[164:167], v230 offset:32768
	ds_read_b128 v[168:171], v230 offset:33792
	ds_read_b128 v[172:175], v230 offset:34816
	ds_read_b128 v[176:179], v230 offset:35840
	ds_read_b128 v[180:183], v230 offset:36864
	ds_read_b128 v[184:187], v230 offset:37888
	ds_read_b128 v[188:191], v230 offset:38912
	ds_read_b128 v[192:195], v230 offset:39936
	global_load_lds_dwordx4 v206, s[42:43]
	s_mov_b32 m0, s47
	s_nop 0
	global_load_lds_dwordx4 v202, s[42:43]
	s_add_u32 s42, s42, 0x80000
	s_addc_u32 s43, s43, 0
	s_mov_b32 m0, s48
	s_nop 0
	global_load_lds_dwordx4 v206, s[42:43]
	s_mov_b32 m0, s49
	s_nop 0
	global_load_lds_dwordx4 v202, s[42:43]
	s_waitcnt vmcnt(8)
	s_waitcnt lgkmcnt(0)
	s_barrier
	s_waitcnt lgkmcnt(0)
	v_mfma_f32_16x16x32_bf16 v[128:131], v[132:135], v[164:167], v[128:131]
	v_mfma_f32_16x16x32_bf16 v[128:131], v[136:139], v[168:171], v[128:131]
	v_mfma_f32_16x16x32_bf16 v[120:123], v[132:135], v[172:175], v[120:123]
	v_mfma_f32_16x16x32_bf16 v[120:123], v[136:139], v[176:179], v[120:123]
	v_mfma_f32_16x16x32_bf16 v[112:115], v[132:135], v[180:183], v[112:115]
	v_mfma_f32_16x16x32_bf16 v[112:115], v[136:139], v[184:187], v[112:115]
	v_mfma_f32_16x16x32_bf16 v[104:107], v[132:135], v[188:191], v[104:107]
	v_mfma_f32_16x16x32_bf16 v[104:107], v[136:139], v[192:195], v[104:107]
	v_mfma_f32_16x16x32_bf16 v[124:127], v[140:143], v[164:167], v[124:127]
	v_mfma_f32_16x16x32_bf16 v[124:127], v[144:147], v[168:171], v[124:127]
	v_mfma_f32_16x16x32_bf16 v[116:119], v[140:143], v[172:175], v[116:119]
	v_mfma_f32_16x16x32_bf16 v[116:119], v[144:147], v[176:179], v[116:119]
	v_mfma_f32_16x16x32_bf16 v[108:111], v[140:143], v[180:183], v[108:111]
	v_mfma_f32_16x16x32_bf16 v[108:111], v[144:147], v[184:187], v[108:111]
	v_mfma_f32_16x16x32_bf16 v[100:103], v[140:143], v[188:191], v[100:103]
	v_mfma_f32_16x16x32_bf16 v[100:103], v[144:147], v[192:195], v[100:103]
	v_mfma_f32_16x16x32_bf16 v[96:99], v[148:151], v[164:167], v[96:99]
	v_mfma_f32_16x16x32_bf16 v[96:99], v[152:155], v[168:171], v[96:99]
	v_mfma_f32_16x16x32_bf16 v[88:91], v[148:151], v[172:175], v[88:91]
	v_mfma_f32_16x16x32_bf16 v[88:91], v[152:155], v[176:179], v[88:91]
	v_mfma_f32_16x16x32_bf16 v[80:83], v[148:151], v[180:183], v[80:83]
	v_mfma_f32_16x16x32_bf16 v[80:83], v[152:155], v[184:187], v[80:83]
	v_mfma_f32_16x16x32_bf16 v[72:75], v[148:151], v[188:191], v[72:75]
	v_mfma_f32_16x16x32_bf16 v[72:75], v[152:155], v[192:195], v[72:75]
	v_mfma_f32_16x16x32_bf16 v[92:95], v[156:159], v[164:167], v[92:95]
	v_mfma_f32_16x16x32_bf16 v[92:95], v[160:163], v[168:171], v[92:95]
	v_mfma_f32_16x16x32_bf16 v[84:87], v[156:159], v[172:175], v[84:87]
	v_mfma_f32_16x16x32_bf16 v[84:87], v[160:163], v[176:179], v[84:87]
	v_mfma_f32_16x16x32_bf16 v[76:79], v[156:159], v[180:183], v[76:79]
	v_mfma_f32_16x16x32_bf16 v[76:79], v[160:163], v[184:187], v[76:79]
	v_mfma_f32_16x16x32_bf16 v[68:71], v[156:159], v[188:191], v[68:71]
	v_mfma_f32_16x16x32_bf16 v[68:71], v[160:163], v[192:195], v[68:71]
	s_barrier
	s_add_i32 s42, s66, s15
	s_add_u32 s98, s34, 0x80
	s_addc_u32 s99, s35, 0
	s_mov_b32 m0, s42
	ds_read_b128 v[164:167], v230 offset:49152
	ds_read_b128 v[168:171], v230 offset:50176
	ds_read_b128 v[172:175], v230 offset:51200
	ds_read_b128 v[176:179], v230 offset:52224
	ds_read_b128 v[180:183], v230 offset:53248
	ds_read_b128 v[184:187], v230 offset:54272
	ds_read_b128 v[188:191], v230 offset:55296
	ds_read_b128 v[192:195], v230 offset:56320
	global_load_lds_dwordx4 v204, s[98:99]
	s_add_i32 m0, s42, 0x2000
	s_add_u32 s34, s34, 0x80080
	s_addc_u32 s35, s35, 0
	s_add_i32 s42, s67, s15
	global_load_lds_dwordx4 v200, s[98:99]
	s_mov_b32 m0, s42
	s_nop 0
	global_load_lds_dwordx4 v204, s[34:35]
	s_add_i32 m0, s42, 0x2000
	s_nop 0
	global_load_lds_dwordx4 v200, s[34:35]
	s_waitcnt vmcnt(6)
	s_waitcnt lgkmcnt(0)
	s_barrier
	s_waitcnt lgkmcnt(0)
	v_mfma_f32_16x16x32_bf16 v[64:67], v[132:135], v[164:167], v[64:67]
	v_mfma_f32_16x16x32_bf16 v[64:67], v[136:139], v[168:171], v[64:67]
	v_mfma_f32_16x16x32_bf16 v[56:59], v[132:135], v[172:175], v[56:59]
	v_mfma_f32_16x16x32_bf16 v[56:59], v[136:139], v[176:179], v[56:59]
	v_mfma_f32_16x16x32_bf16 v[48:51], v[132:135], v[180:183], v[48:51]
	v_mfma_f32_16x16x32_bf16 v[48:51], v[136:139], v[184:187], v[48:51]
	v_mfma_f32_16x16x32_bf16 v[40:43], v[132:135], v[188:191], v[40:43]
	v_mfma_f32_16x16x32_bf16 v[40:43], v[136:139], v[192:195], v[40:43]
	v_mfma_f32_16x16x32_bf16 v[60:63], v[140:143], v[164:167], v[60:63]
	v_mfma_f32_16x16x32_bf16 v[60:63], v[144:147], v[168:171], v[60:63]
	v_mfma_f32_16x16x32_bf16 v[52:55], v[140:143], v[172:175], v[52:55]
	v_mfma_f32_16x16x32_bf16 v[52:55], v[144:147], v[176:179], v[52:55]
	s_add_i32 s57, s57, 2
	v_mfma_f32_16x16x32_bf16 v[44:47], v[140:143], v[180:183], v[44:47]
	v_mfma_f32_16x16x32_bf16 v[44:47], v[144:147], v[184:187], v[44:47]
	s_add_u32 s30, s30, 0x100
	s_addc_u32 s31, s31, 0
	v_mfma_f32_16x16x32_bf16 v[36:39], v[140:143], v[188:191], v[36:39]
	v_mfma_f32_16x16x32_bf16 v[36:39], v[144:147], v[192:195], v[36:39]
	s_add_u32 s55, s55, 0x100
	s_addc_u32 s56, s56, 0
	v_mfma_f32_16x16x32_bf16 v[32:35], v[148:151], v[164:167], v[32:35]
	v_mfma_f32_16x16x32_bf16 v[32:35], v[152:155], v[168:171], v[32:35]
	s_add_u32 s98, s30, 0xfff80000
	s_addc_u32 s99, s31, -1
	v_mfma_f32_16x16x32_bf16 v[28:31], v[156:159], v[164:167], v[28:31]
	v_mfma_f32_16x16x32_bf16 v[28:31], v[160:163], v[168:171], v[28:31]
	s_add_u32 s34, s30, 0xfff80080
	s_addc_u32 s35, s31, -1
	v_mfma_f32_16x16x32_bf16 v[24:27], v[148:151], v[172:175], v[24:27]
	v_mfma_f32_16x16x32_bf16 v[24:27], v[152:155], v[176:179], v[24:27]
	s_add_i32 s66, 0, 0x10000
	v_mfma_f32_16x16x32_bf16 v[20:23], v[156:159], v[172:175], v[20:23]
	v_mfma_f32_16x16x32_bf16 v[20:23], v[160:163], v[176:179], v[20:23]
	s_cmp_eq_u32 s57, 28
	s_cselect_b32 s43, s19, s35
	s_cselect_b32 s42, s23, s34
	s_cselect_b32 s35, s25, s56
	s_cselect_b32 s34, s54, s55
	v_mfma_f32_16x16x32_bf16 v[16:19], v[148:151], v[180:183], v[16:19]
	v_mfma_f32_16x16x32_bf16 v[16:19], v[152:155], v[184:187], v[16:19]
	s_add_i32 s73, 0, 0x14000
	v_mfma_f32_16x16x32_bf16 v[12:15], v[156:159], v[180:183], v[12:15]
	v_mfma_f32_16x16x32_bf16 v[12:15], v[160:163], v[184:187], v[12:15]
	s_cmp_gt_u32 s57, 29
	v_mfma_f32_16x16x32_bf16 v[6:9], v[148:151], v[188:191], v[8:11]
	v_mfma_f32_16x16x32_bf16 v[8:11], v[152:155], v[192:195], v[6:9]
	v_mfma_f32_16x16x32_bf16 v[2:5], v[156:159], v[188:191], v[2:5]
	v_mfma_f32_16x16x32_bf16 v[4:7], v[160:163], v[192:195], v[2:5]
	s_barrier
	s_cbranch_scc0 .Lkb_577
	s_and_b64 vcc, exec, s[20:21]
	s_cbranch_vccz .LBB0_580
	s_barrier

.Lkb_779:
	v_add_u32_e32 v114, s66, v157
	v_add_u32_e32 v156, s73, v157
	ds_read_b128 v[90:93], v114
	ds_read_b128 v[94:97], v114 offset:1024
	ds_read_b128 v[106:109], v114 offset:2048
	ds_read_b128 v[114:117], v114 offset:3072
	ds_read_b128 v[162:165], v156
	ds_read_b128 v[166:169], v156 offset:1024
	ds_read_b128 v[170:173], v156 offset:2048
	ds_read_b128 v[174:177], v156 offset:3072
	s_mov_b32 m0, s50
	ds_read_b128 v[178:181], v161
	ds_read_b128 v[182:185], v161 offset:1024
	ds_read_b128 v[186:189], v161 offset:2048
	ds_read_b128 v[190:193], v161 offset:3072
	ds_read_b128 v[200:203], v161 offset:4096
	ds_read_b128 v[204:207], v161 offset:5120
	ds_read_b128 v[208:211], v161 offset:6144
	ds_read_b128 v[212:215], v161 offset:7168
	global_load_lds_dwordx4 v150, s[98:99]
	s_mov_b32 m0, s51
	s_nop 0
	global_load_lds_dwordx4 v148, s[98:99]
	s_add_i32 m0, s14, 0xc000
	s_nop 0
	global_load_lds_dwordx4 v152, s[30:31]
	s_add_i32 m0, s14, 0xe000
	s_nop 0
	global_load_lds_dwordx4 v154, s[30:31]
	s_waitcnt vmcnt(8)
	s_waitcnt lgkmcnt(0)
	s_barrier
	s_waitcnt lgkmcnt(0)
	v_mfma_i32_16x16x64_i8 v[142:145], v[90:93], v[178:181], v[142:145]
	v_mfma_i32_16x16x64_i8 v[142:145], v[94:97], v[182:185], v[142:145]
	v_mfma_i32_16x16x64_i8 v[126:129], v[90:93], v[186:189], v[126:129]
	v_mfma_i32_16x16x64_i8 v[126:129], v[94:97], v[190:193], v[126:129]
	v_mfma_i32_16x16x64_i8 v[102:105], v[90:93], v[200:203], v[102:105]
	v_mfma_i32_16x16x64_i8 v[102:105], v[94:97], v[204:207], v[102:105]
	v_mfma_i32_16x16x64_i8 v[78:81], v[90:93], v[208:211], v[78:81]
	v_mfma_i32_16x16x64_i8 v[78:81], v[94:97], v[212:215], v[78:81]
	v_mfma_i32_16x16x64_i8 v[138:141], v[106:109], v[178:181], v[138:141]
	v_mfma_i32_16x16x64_i8 v[138:141], v[114:117], v[182:185], v[138:141]
	v_mfma_i32_16x16x64_i8 v[122:125], v[106:109], v[186:189], v[122:125]
	v_mfma_i32_16x16x64_i8 v[122:125], v[114:117], v[190:193], v[122:125]
	v_mfma_i32_16x16x64_i8 v[98:101], v[106:109], v[200:203], v[98:101]
	v_mfma_i32_16x16x64_i8 v[98:101], v[114:117], v[204:207], v[98:101]
	v_mfma_i32_16x16x64_i8 v[74:77], v[106:109], v[208:211], v[74:77]
	v_mfma_i32_16x16x64_i8 v[74:77], v[114:117], v[212:215], v[74:77]
	v_mfma_i32_16x16x64_i8 v[134:137], v[162:165], v[178:181], v[134:137]
	v_mfma_i32_16x16x64_i8 v[134:137], v[166:169], v[182:185], v[134:137]
	v_mfma_i32_16x16x64_i8 v[118:121], v[162:165], v[186:189], v[118:121]
	v_mfma_i32_16x16x64_i8 v[118:121], v[166:169], v[190:193], v[118:121]
	v_mfma_i32_16x16x64_i8 v[86:89], v[162:165], v[200:203], v[86:89]
	v_mfma_i32_16x16x64_i8 v[86:89], v[166:169], v[204:207], v[86:89]
	v_mfma_i32_16x16x64_i8 v[70:73], v[162:165], v[208:211], v[70:73]
	v_mfma_i32_16x16x64_i8 v[70:73], v[166:169], v[212:215], v[70:73]
	v_mfma_i32_16x16x64_i8 v[130:133], v[170:173], v[178:181], v[130:133]
	v_mfma_i32_16x16x64_i8 v[130:133], v[174:177], v[182:185], v[130:133]
	v_mfma_i32_16x16x64_i8 v[110:113], v[170:173], v[186:189], v[110:113]
	v_mfma_i32_16x16x64_i8 v[110:113], v[174:177], v[190:193], v[110:113]
	v_mfma_i32_16x16x64_i8 v[82:85], v[170:173], v[200:203], v[82:85]
	v_mfma_i32_16x16x64_i8 v[82:85], v[174:177], v[204:207], v[82:85]
	v_mfma_i32_16x16x64_i8 v[66:69], v[170:173], v[208:211], v[66:69]
	v_mfma_i32_16x16x64_i8 v[66:69], v[174:177], v[212:215], v[66:69]
	s_barrier
	s_add_i32 s66, s66, s9
	s_mov_b32 m0, s66
	ds_read_b128 v[178:181], v161 offset:16384
	ds_read_b128 v[182:185], v161 offset:17408
	ds_read_b128 v[186:189], v161 offset:18432
	ds_read_b128 v[190:193], v161 offset:19456
	ds_read_b128 v[200:203], v161 offset:20480
	ds_read_b128 v[204:207], v161 offset:21504
	ds_read_b128 v[208:211], v161 offset:22528
	ds_read_b128 v[212:215], v161 offset:23552
	global_load_lds_dwordx4 v0, s[34:35]
	s_add_i32 m0, s66, 0x2000
	s_add_u32 s66, s34, 0x80000
	s_addc_u32 s67, s35, 0
	s_add_i32 s73, s73, s9
	global_load_lds_dwordx4 v146, s[34:35]
	s_mov_b32 m0, s73
	s_nop 0
	global_load_lds_dwordx4 v0, s[66:67]
	s_add_i32 m0, s73, 0x2000
	s_nop 0
	global_load_lds_dwordx4 v146, s[66:67]
	s_waitcnt vmcnt(6)
	s_waitcnt lgkmcnt(0)
	s_barrier
	s_waitcnt lgkmcnt(0)
	v_mfma_i32_16x16x64_i8 v[62:65], v[90:93], v[178:181], v[62:65]
	v_mfma_i32_16x16x64_i8 v[62:65], v[94:97], v[182:185], v[62:65]
	v_mfma_i32_16x16x64_i8 v[46:49], v[90:93], v[186:189], v[46:49]
	v_mfma_i32_16x16x64_i8 v[46:49], v[94:97], v[190:193], v[46:49]
	v_mfma_i32_16x16x64_i8 v[30:33], v[90:93], v[200:203], v[30:33]
	v_mfma_i32_16x16x64_i8 v[30:33], v[94:97], v[204:207], v[30:33]
	v_mfma_i32_16x16x64_i8 v[14:17], v[90:93], v[208:211], v[14:17]
	v_mfma_i32_16x16x64_i8 v[14:17], v[94:97], v[212:215], v[14:17]
	v_mfma_i32_16x16x64_i8 v[58:61], v[106:109], v[178:181], v[58:61]
	v_mfma_i32_16x16x64_i8 v[58:61], v[114:117], v[182:185], v[58:61]
	v_mfma_i32_16x16x64_i8 v[42:45], v[106:109], v[186:189], v[42:45]
	v_mfma_i32_16x16x64_i8 v[42:45], v[114:117], v[190:193], v[42:45]
	v_mfma_i32_16x16x64_i8 v[26:29], v[106:109], v[200:203], v[26:29]
	v_mfma_i32_16x16x64_i8 v[26:29], v[114:117], v[204:207], v[26:29]
	v_mfma_i32_16x16x64_i8 v[10:13], v[106:109], v[208:211], v[10:13]
	v_mfma_i32_16x16x64_i8 v[10:13], v[114:117], v[212:215], v[10:13]
	v_mfma_i32_16x16x64_i8 v[54:57], v[162:165], v[178:181], v[54:57]
	v_mfma_i32_16x16x64_i8 v[54:57], v[166:169], v[182:185], v[54:57]
	v_mfma_i32_16x16x64_i8 v[38:41], v[162:165], v[186:189], v[38:41]
	v_mfma_i32_16x16x64_i8 v[38:41], v[166:169], v[190:193], v[38:41]
	v_mfma_i32_16x16x64_i8 v[22:25], v[162:165], v[200:203], v[22:25]
	v_mfma_i32_16x16x64_i8 v[22:25], v[166:169], v[204:207], v[22:25]
	v_mfma_i32_16x16x64_i8 v[6:9], v[162:165], v[208:211], v[6:9]
	v_mfma_i32_16x16x64_i8 v[6:9], v[166:169], v[212:215], v[6:9]
	v_mfma_i32_16x16x64_i8 v[50:53], v[170:173], v[178:181], v[50:53]
	v_mfma_i32_16x16x64_i8 v[50:53], v[174:177], v[182:185], v[50:53]
	v_mfma_i32_16x16x64_i8 v[34:37], v[170:173], v[186:189], v[34:37]
	v_mfma_i32_16x16x64_i8 v[34:37], v[174:177], v[190:193], v[34:37]
	v_mfma_i32_16x16x64_i8 v[18:21], v[170:173], v[200:203], v[18:21]
	v_mfma_i32_16x16x64_i8 v[18:21], v[174:177], v[204:207], v[18:21]
	v_mfma_i32_16x16x64_i8 v[2:5], v[170:173], v[208:211], v[2:5]
	v_mfma_i32_16x16x64_i8 v[2:5], v[174:177], v[212:215], v[2:5]
	s_barrier
	s_add_i32 s66, 0, 0x18000
	s_add_i32 s67, 0, 0x1c000
	v_add_u32_e32 v114, s66, v157
	v_add_u32_e32 v156, s67, v157
	ds_read_b128 v[90:93], v114
	ds_read_b128 v[94:97], v114 offset:1024
	ds_read_b128 v[106:109], v114 offset:2048
	ds_read_b128 v[114:117], v114 offset:3072
	ds_read_b128 v[162:165], v156
	ds_read_b128 v[166:169], v156 offset:1024
	ds_read_b128 v[170:173], v156 offset:2048
	ds_read_b128 v[174:177], v156 offset:3072
	s_mov_b32 m0, s14
	ds_read_b128 v[178:181], v161 offset:32768
	ds_read_b128 v[182:185], v161 offset:33792
	ds_read_b128 v[186:189], v161 offset:34816
	ds_read_b128 v[190:193], v161 offset:35840
	ds_read_b128 v[200:203], v161 offset:36864
	ds_read_b128 v[204:207], v161 offset:37888
	ds_read_b128 v[208:211], v161 offset:38912
	ds_read_b128 v[212:215], v161 offset:39936
	global_load_lds_dwordx4 v150, s[42:43]
	s_mov_b32 m0, s15
	s_nop 0
	global_load_lds_dwordx4 v148, s[42:43]
	s_add_u32 s42, s42, 0x80000
	s_addc_u32 s43, s43, 0
	s_mov_b32 m0, s46
	s_nop 0
	global_load_lds_dwordx4 v150, s[42:43]
	s_mov_b32 m0, s47
	s_nop 0
	global_load_lds_dwordx4 v148, s[42:43]
	s_waitcnt vmcnt(8)
	s_waitcnt lgkmcnt(0)
	s_barrier
	s_waitcnt lgkmcnt(0)
	v_mfma_i32_16x16x64_i8 v[142:145], v[90:93], v[178:181], v[142:145]
	v_mfma_i32_16x16x64_i8 v[142:145], v[94:97], v[182:185], v[142:145]
	v_mfma_i32_16x16x64_i8 v[126:129], v[90:93], v[186:189], v[126:129]
	v_mfma_i32_16x16x64_i8 v[126:129], v[94:97], v[190:193], v[126:129]
	v_mfma_i32_16x16x64_i8 v[102:105], v[90:93], v[200:203], v[102:105]
	v_mfma_i32_16x16x64_i8 v[102:105], v[94:97], v[204:207], v[102:105]
	v_mfma_i32_16x16x64_i8 v[78:81], v[90:93], v[208:211], v[78:81]
	v_mfma_i32_16x16x64_i8 v[78:81], v[94:97], v[212:215], v[78:81]
	v_mfma_i32_16x16x64_i8 v[138:141], v[106:109], v[178:181], v[138:141]
	v_mfma_i32_16x16x64_i8 v[138:141], v[114:117], v[182:185], v[138:141]
	v_mfma_i32_16x16x64_i8 v[122:125], v[106:109], v[186:189], v[122:125]
	v_mfma_i32_16x16x64_i8 v[122:125], v[114:117], v[190:193], v[122:125]
	v_mfma_i32_16x16x64_i8 v[98:101], v[106:109], v[200:203], v[98:101]
	v_mfma_i32_16x16x64_i8 v[98:101], v[114:117], v[204:207], v[98:101]
	v_mfma_i32_16x16x64_i8 v[74:77], v[106:109], v[208:211], v[74:77]
	v_mfma_i32_16x16x64_i8 v[74:77], v[114:117], v[212:215], v[74:77]
	v_mfma_i32_16x16x64_i8 v[134:137], v[162:165], v[178:181], v[134:137]
	v_mfma_i32_16x16x64_i8 v[134:137], v[166:169], v[182:185], v[134:137]
	v_mfma_i32_16x16x64_i8 v[118:121], v[162:165], v[186:189], v[118:121]
	v_mfma_i32_16x16x64_i8 v[118:121], v[166:169], v[190:193], v[118:121]
	v_mfma_i32_16x16x64_i8 v[86:89], v[162:165], v[200:203], v[86:89]
	v_mfma_i32_16x16x64_i8 v[86:89], v[166:169], v[204:207], v[86:89]
	v_mfma_i32_16x16x64_i8 v[70:73], v[162:165], v[208:211], v[70:73]
	v_mfma_i32_16x16x64_i8 v[70:73], v[166:169], v[212:215], v[70:73]
	v_mfma_i32_16x16x64_i8 v[130:133], v[170:173], v[178:181], v[130:133]
	v_mfma_i32_16x16x64_i8 v[130:133], v[174:177], v[182:185], v[130:133]
	v_mfma_i32_16x16x64_i8 v[110:113], v[170:173], v[186:189], v[110:113]
	v_mfma_i32_16x16x64_i8 v[110:113], v[174:177], v[190:193], v[110:113]
	v_mfma_i32_16x16x64_i8 v[82:85], v[170:173], v[200:203], v[82:85]
	v_mfma_i32_16x16x64_i8 v[82:85], v[174:177], v[204:207], v[82:85]
	v_mfma_i32_16x16x64_i8 v[66:69], v[170:173], v[208:211], v[66:69]
	v_mfma_i32_16x16x64_i8 v[66:69], v[174:177], v[212:215], v[66:69]
	s_barrier
	s_add_u32 s98, s34, 0x80
	s_addc_u32 s99, s35, 0
	s_add_i32 s42, s66, s9
	s_mov_b32 m0, s42
	ds_read_b128 v[178:181], v161 offset:49152
	ds_read_b128 v[182:185], v161 offset:50176
	ds_read_b128 v[186:189], v161 offset:51200
	ds_read_b128 v[190:193], v161 offset:52224
	ds_read_b128 v[200:203], v161 offset:53248
	ds_read_b128 v[204:207], v161 offset:54272
	ds_read_b128 v[208:211], v161 offset:55296
	ds_read_b128 v[212:215], v161 offset:56320
	global_load_lds_dwordx4 v0, s[98:99]
	s_add_i32 m0, s42, 0x2000
	s_add_u32 s34, s34, 0x80080
	s_addc_u32 s35, s35, 0
	s_add_i32 s42, s67, s9
	global_load_lds_dwordx4 v146, s[98:99]
	s_mov_b32 m0, s42
	s_nop 0
	global_load_lds_dwordx4 v0, s[34:35]
	s_add_i32 m0, s42, 0x2000
	s_nop 0
	global_load_lds_dwordx4 v146, s[34:35]
	s_waitcnt vmcnt(6)
	s_waitcnt lgkmcnt(0)
	s_barrier
	s_waitcnt lgkmcnt(0)
	v_mfma_i32_16x16x64_i8 v[62:65], v[90:93], v[178:181], v[62:65]
	v_mfma_i32_16x16x64_i8 v[62:65], v[94:97], v[182:185], v[62:65]
	v_mfma_i32_16x16x64_i8 v[46:49], v[90:93], v[186:189], v[46:49]
	v_mfma_i32_16x16x64_i8 v[46:49], v[94:97], v[190:193], v[46:49]
	v_mfma_i32_16x16x64_i8 v[30:33], v[90:93], v[200:203], v[30:33]
	v_mfma_i32_16x16x64_i8 v[30:33], v[94:97], v[204:207], v[30:33]
	v_mfma_i32_16x16x64_i8 v[14:17], v[90:93], v[208:211], v[14:17]
	v_mfma_i32_16x16x64_i8 v[14:17], v[94:97], v[212:215], v[14:17]
	v_mfma_i32_16x16x64_i8 v[58:61], v[106:109], v[178:181], v[58:61]
	v_mfma_i32_16x16x64_i8 v[58:61], v[114:117], v[182:185], v[58:61]
	v_mfma_i32_16x16x64_i8 v[42:45], v[106:109], v[186:189], v[42:45]
	v_mfma_i32_16x16x64_i8 v[42:45], v[114:117], v[190:193], v[42:45]
	s_add_i32 s57, s57, 2
	v_mfma_i32_16x16x64_i8 v[26:29], v[106:109], v[200:203], v[26:29]
	v_mfma_i32_16x16x64_i8 v[26:29], v[114:117], v[204:207], v[26:29]
	s_add_u32 s30, s30, 0x100
	s_addc_u32 s31, s31, 0
	v_mfma_i32_16x16x64_i8 v[10:13], v[106:109], v[208:211], v[10:13]
	v_mfma_i32_16x16x64_i8 v[10:13], v[114:117], v[212:215], v[10:13]
	s_add_u32 s55, s55, 0x100
	s_addc_u32 s56, s56, 0
	v_mfma_i32_16x16x64_i8 v[54:57], v[162:165], v[178:181], v[54:57]
	v_mfma_i32_16x16x64_i8 v[54:57], v[166:169], v[182:185], v[54:57]
	s_add_u32 s98, s30, 0xfff80000
	s_addc_u32 s99, s31, -1
	v_mfma_i32_16x16x64_i8 v[38:41], v[162:165], v[186:189], v[38:41]
	v_mfma_i32_16x16x64_i8 v[38:41], v[166:169], v[190:193], v[38:41]
	s_add_u32 s34, s30, 0xfff80080
	s_addc_u32 s35, s31, -1
	v_mfma_i32_16x16x64_i8 v[22:25], v[162:165], v[200:203], v[22:25]
	v_mfma_i32_16x16x64_i8 v[22:25], v[166:169], v[204:207], v[22:25]
	s_add_i32 s66, 0, 0x10000
	v_mfma_i32_16x16x64_i8 v[6:9], v[162:165], v[208:211], v[6:9]
	v_mfma_i32_16x16x64_i8 v[6:9], v[166:169], v[212:215], v[6:9]
	s_cmp_eq_u32 s57, 28
	s_cselect_b32 s43, s25, s35
	s_cselect_b32 s42, s53, s34
	s_cselect_b32 s35, s23, s56
	s_cselect_b32 s34, s54, s55
	v_mfma_i32_16x16x64_i8 v[50:53], v[170:173], v[178:181], v[50:53]
	v_mfma_i32_16x16x64_i8 v[50:53], v[174:177], v[182:185], v[50:53]
	s_add_i32 s73, 0, 0x14000
	v_mfma_i32_16x16x64_i8 v[34:37], v[170:173], v[186:189], v[34:37]
	v_mfma_i32_16x16x64_i8 v[34:37], v[174:177], v[190:193], v[34:37]
	s_cmp_gt_u32 s57, 29
	v_mfma_i32_16x16x64_i8 v[18:21], v[170:173], v[200:203], v[18:21]
	v_mfma_i32_16x16x64_i8 v[18:21], v[174:177], v[204:207], v[18:21]
	v_mfma_i32_16x16x64_i8 v[2:5], v[170:173], v[208:211], v[2:5]
	v_mfma_i32_16x16x64_i8 v[2:5], v[174:177], v[212:215], v[2:5]
	s_barrier
	s_cbranch_scc0 .Lkb_779
	s_and_b64 vcc, exec, s[20:21]
	s_mov_b32 s54, 0x5c401000
	s_cbranch_vccz .LBB0_782
	s_barrier

.Lkb_801:
	v_add_u32_e32 v156, s54, v141
	v_add_u32_e32 v172, s56, v141
	ds_read_b128 v[144:147], v156
	ds_read_b128 v[148:151], v156 offset:1024
	ds_read_b128 v[152:155], v156 offset:2048
	ds_read_b128 v[156:159], v156 offset:3072
	ds_read_b128 v[160:163], v172
	ds_read_b128 v[164:167], v172 offset:1024
	ds_read_b128 v[168:171], v172 offset:2048
	ds_read_b128 v[172:175], v172 offset:3072
	s_mov_b32 m0, s42
	ds_read_b128 v[176:179], v143
	ds_read_b128 v[180:183], v143 offset:1024
	ds_read_b128 v[184:187], v143 offset:2048
	ds_read_b128 v[188:191], v143 offset:3072
	ds_read_b128 v[192:195], v143 offset:4096
	ds_read_b128 v[200:203], v143 offset:5120
	ds_read_b128 v[204:207], v143 offset:6144
	ds_read_b128 v[208:211], v143 offset:7168
	global_load_lds_dwordx4 v134, s[98:99]
	s_mov_b32 m0, s43
	s_nop 0
	global_load_lds_dwordx4 v132, s[98:99]
	s_add_i32 m0, s14, 0xc000
	s_nop 0
	global_load_lds_dwordx4 v136, s[30:31]
	s_add_i32 m0, s14, 0xe000
	s_nop 0
	global_load_lds_dwordx4 v138, s[30:31]
	s_waitcnt vmcnt(8)
	s_waitcnt lgkmcnt(0)
	s_barrier
	s_waitcnt lgkmcnt(0)
	v_mfma_f32_16x16x32_bf16 v[126:129], v[144:147], v[176:179], v[126:129]
	v_mfma_f32_16x16x32_bf16 v[126:129], v[148:151], v[180:183], v[126:129]
	v_mfma_f32_16x16x32_bf16 v[118:121], v[144:147], v[184:187], v[118:121]
	v_mfma_f32_16x16x32_bf16 v[118:121], v[148:151], v[188:191], v[118:121]
	v_mfma_f32_16x16x32_bf16 v[102:105], v[144:147], v[192:195], v[102:105]
	v_mfma_f32_16x16x32_bf16 v[102:105], v[148:151], v[200:203], v[102:105]
	v_mfma_f32_16x16x32_bf16 v[86:89], v[144:147], v[204:207], v[86:89]
	v_mfma_f32_16x16x32_bf16 v[86:89], v[148:151], v[208:211], v[86:89]
	v_mfma_f32_16x16x32_bf16 v[122:125], v[152:155], v[176:179], v[122:125]
	v_mfma_f32_16x16x32_bf16 v[122:125], v[156:159], v[180:183], v[122:125]
	v_mfma_f32_16x16x32_bf16 v[114:117], v[152:155], v[184:187], v[114:117]
	v_mfma_f32_16x16x32_bf16 v[114:117], v[156:159], v[188:191], v[114:117]
	v_mfma_f32_16x16x32_bf16 v[98:101], v[152:155], v[192:195], v[98:101]
	v_mfma_f32_16x16x32_bf16 v[98:101], v[156:159], v[200:203], v[98:101]
	v_mfma_f32_16x16x32_bf16 v[82:85], v[152:155], v[204:207], v[82:85]
	v_mfma_f32_16x16x32_bf16 v[82:85], v[156:159], v[208:211], v[82:85]
	v_mfma_f32_16x16x32_bf16 v[110:113], v[160:163], v[176:179], v[110:113]
	v_mfma_f32_16x16x32_bf16 v[110:113], v[164:167], v[180:183], v[110:113]
	v_mfma_f32_16x16x32_bf16 v[94:97], v[160:163], v[184:187], v[94:97]
	v_mfma_f32_16x16x32_bf16 v[94:97], v[164:167], v[188:191], v[94:97]
	v_mfma_f32_16x16x32_bf16 v[78:81], v[160:163], v[192:195], v[78:81]
	v_mfma_f32_16x16x32_bf16 v[78:81], v[164:167], v[200:203], v[78:81]
	v_mfma_f32_16x16x32_bf16 v[70:73], v[160:163], v[204:207], v[70:73]
	v_mfma_f32_16x16x32_bf16 v[70:73], v[164:167], v[208:211], v[70:73]
	v_mfma_f32_16x16x32_bf16 v[106:109], v[168:171], v[176:179], v[106:109]
	v_mfma_f32_16x16x32_bf16 v[106:109], v[172:175], v[180:183], v[106:109]
	v_mfma_f32_16x16x32_bf16 v[90:93], v[168:171], v[184:187], v[90:93]
	v_mfma_f32_16x16x32_bf16 v[90:93], v[172:175], v[188:191], v[90:93]
	v_mfma_f32_16x16x32_bf16 v[74:77], v[168:171], v[192:195], v[74:77]
	v_mfma_f32_16x16x32_bf16 v[74:77], v[172:175], v[200:203], v[74:77]
	v_mfma_f32_16x16x32_bf16 v[66:69], v[168:171], v[204:207], v[66:69]
	v_mfma_f32_16x16x32_bf16 v[66:69], v[172:175], v[208:211], v[66:69]
	s_barrier
	s_add_i32 s54, s54, s9
	s_mov_b32 m0, s54
	ds_read_b128 v[176:179], v143 offset:16384
	ds_read_b128 v[180:183], v143 offset:17408
	ds_read_b128 v[184:187], v143 offset:18432
	ds_read_b128 v[188:191], v143 offset:19456
	ds_read_b128 v[192:195], v143 offset:20480
	ds_read_b128 v[200:203], v143 offset:21504
	ds_read_b128 v[204:207], v143 offset:22528
	ds_read_b128 v[208:211], v143 offset:23552
	global_load_lds_dwordx4 v0, s[34:35]
	s_add_i32 m0, s54, 0x2000
	s_add_u32 s54, s34, 0x100000
	s_addc_u32 s55, s35, 0
	s_add_i32 s56, s56, s9
	global_load_lds_dwordx4 v130, s[34:35]
	s_mov_b32 m0, s56
	s_nop 0
	global_load_lds_dwordx4 v0, s[54:55]
	s_add_i32 m0, s56, 0x2000
	s_nop 0
	global_load_lds_dwordx4 v130, s[54:55]
	s_waitcnt vmcnt(6)
	s_waitcnt lgkmcnt(0)
	s_barrier
	s_waitcnt lgkmcnt(0)
	v_mfma_f32_16x16x32_bf16 v[62:65], v[144:147], v[176:179], v[62:65]
	v_mfma_f32_16x16x32_bf16 v[62:65], v[148:151], v[180:183], v[62:65]
	v_mfma_f32_16x16x32_bf16 v[54:57], v[144:147], v[184:187], v[54:57]
	v_mfma_f32_16x16x32_bf16 v[54:57], v[148:151], v[188:191], v[54:57]
	v_mfma_f32_16x16x32_bf16 v[38:41], v[144:147], v[192:195], v[38:41]
	v_mfma_f32_16x16x32_bf16 v[38:41], v[148:151], v[200:203], v[38:41]
	v_mfma_f32_16x16x32_bf16 v[22:25], v[144:147], v[204:207], v[22:25]
	v_mfma_f32_16x16x32_bf16 v[22:25], v[148:151], v[208:211], v[22:25]
	v_mfma_f32_16x16x32_bf16 v[58:61], v[152:155], v[176:179], v[58:61]
	v_mfma_f32_16x16x32_bf16 v[58:61], v[156:159], v[180:183], v[58:61]
	v_mfma_f32_16x16x32_bf16 v[50:53], v[152:155], v[184:187], v[50:53]
	v_mfma_f32_16x16x32_bf16 v[50:53], v[156:159], v[188:191], v[50:53]
	v_mfma_f32_16x16x32_bf16 v[34:37], v[152:155], v[192:195], v[34:37]
	v_mfma_f32_16x16x32_bf16 v[34:37], v[156:159], v[200:203], v[34:37]
	v_mfma_f32_16x16x32_bf16 v[18:21], v[152:155], v[204:207], v[18:21]
	v_mfma_f32_16x16x32_bf16 v[18:21], v[156:159], v[208:211], v[18:21]
	v_mfma_f32_16x16x32_bf16 v[46:49], v[160:163], v[176:179], v[46:49]
	v_mfma_f32_16x16x32_bf16 v[46:49], v[164:167], v[180:183], v[46:49]
	v_mfma_f32_16x16x32_bf16 v[30:33], v[160:163], v[184:187], v[30:33]
	v_mfma_f32_16x16x32_bf16 v[30:33], v[164:167], v[188:191], v[30:33]
	v_mfma_f32_16x16x32_bf16 v[14:17], v[160:163], v[192:195], v[14:17]
	v_mfma_f32_16x16x32_bf16 v[14:17], v[164:167], v[200:203], v[14:17]
	v_mfma_f32_16x16x32_bf16 v[6:9], v[160:163], v[204:207], v[6:9]
	v_mfma_f32_16x16x32_bf16 v[6:9], v[164:167], v[208:211], v[6:9]
	v_mfma_f32_16x16x32_bf16 v[42:45], v[168:171], v[176:179], v[42:45]
	v_mfma_f32_16x16x32_bf16 v[42:45], v[172:175], v[180:183], v[42:45]
	v_mfma_f32_16x16x32_bf16 v[26:29], v[168:171], v[184:187], v[26:29]
	v_mfma_f32_16x16x32_bf16 v[26:29], v[172:175], v[188:191], v[26:29]
	v_mfma_f32_16x16x32_bf16 v[10:13], v[168:171], v[192:195], v[10:13]
	v_mfma_f32_16x16x32_bf16 v[10:13], v[172:175], v[200:203], v[10:13]
	v_mfma_f32_16x16x32_bf16 v[2:5], v[168:171], v[204:207], v[2:5]
	v_mfma_f32_16x16x32_bf16 v[2:5], v[172:175], v[208:211], v[2:5]
	s_barrier
	s_add_i32 s54, 0, 0x18000
	s_add_i32 s55, 0, 0x1c000
	v_add_u32_e32 v156, s54, v141
	v_add_u32_e32 v172, s55, v141
	ds_read_b128 v[144:147], v156
	ds_read_b128 v[148:151], v156 offset:1024
	ds_read_b128 v[152:155], v156 offset:2048
	ds_read_b128 v[156:159], v156 offset:3072
	ds_read_b128 v[160:163], v172
	ds_read_b128 v[164:167], v172 offset:1024
	ds_read_b128 v[168:171], v172 offset:2048
	ds_read_b128 v[172:175], v172 offset:3072
	s_mov_b32 m0, s14
	ds_read_b128 v[176:179], v143 offset:32768
	ds_read_b128 v[180:183], v143 offset:33792
	ds_read_b128 v[184:187], v143 offset:34816
	ds_read_b128 v[188:191], v143 offset:35840
	ds_read_b128 v[192:195], v143 offset:36864
	ds_read_b128 v[200:203], v143 offset:37888
	ds_read_b128 v[204:207], v143 offset:38912
	ds_read_b128 v[208:211], v143 offset:39936
	global_load_lds_dwordx4 v134, s[40:41]
	s_mov_b32 m0, s15
	s_nop 0
	global_load_lds_dwordx4 v132, s[40:41]
	s_add_u32 s40, s40, 0x100000
	s_addc_u32 s41, s41, 0
	s_mov_b32 m0, s18
	s_nop 0
	global_load_lds_dwordx4 v134, s[40:41]
	s_mov_b32 m0, s19
	s_nop 0
	global_load_lds_dwordx4 v132, s[40:41]
	s_waitcnt vmcnt(8)
	s_waitcnt lgkmcnt(0)
	s_barrier
	s_waitcnt lgkmcnt(0)
	v_mfma_f32_16x16x32_bf16 v[126:129], v[144:147], v[176:179], v[126:129]
	v_mfma_f32_16x16x32_bf16 v[126:129], v[148:151], v[180:183], v[126:129]
	v_mfma_f32_16x16x32_bf16 v[118:121], v[144:147], v[184:187], v[118:121]
	v_mfma_f32_16x16x32_bf16 v[118:121], v[148:151], v[188:191], v[118:121]
	v_mfma_f32_16x16x32_bf16 v[102:105], v[144:147], v[192:195], v[102:105]
	v_mfma_f32_16x16x32_bf16 v[102:105], v[148:151], v[200:203], v[102:105]
	v_mfma_f32_16x16x32_bf16 v[86:89], v[144:147], v[204:207], v[86:89]
	v_mfma_f32_16x16x32_bf16 v[86:89], v[148:151], v[208:211], v[86:89]
	v_mfma_f32_16x16x32_bf16 v[122:125], v[152:155], v[176:179], v[122:125]
	v_mfma_f32_16x16x32_bf16 v[122:125], v[156:159], v[180:183], v[122:125]
	v_mfma_f32_16x16x32_bf16 v[114:117], v[152:155], v[184:187], v[114:117]
	v_mfma_f32_16x16x32_bf16 v[114:117], v[156:159], v[188:191], v[114:117]
	v_mfma_f32_16x16x32_bf16 v[98:101], v[152:155], v[192:195], v[98:101]
	v_mfma_f32_16x16x32_bf16 v[98:101], v[156:159], v[200:203], v[98:101]
	v_mfma_f32_16x16x32_bf16 v[82:85], v[152:155], v[204:207], v[82:85]
	v_mfma_f32_16x16x32_bf16 v[82:85], v[156:159], v[208:211], v[82:85]
	v_mfma_f32_16x16x32_bf16 v[110:113], v[160:163], v[176:179], v[110:113]
	v_mfma_f32_16x16x32_bf16 v[110:113], v[164:167], v[180:183], v[110:113]
	v_mfma_f32_16x16x32_bf16 v[94:97], v[160:163], v[184:187], v[94:97]
	v_mfma_f32_16x16x32_bf16 v[94:97], v[164:167], v[188:191], v[94:97]
	v_mfma_f32_16x16x32_bf16 v[78:81], v[160:163], v[192:195], v[78:81]
	v_mfma_f32_16x16x32_bf16 v[78:81], v[164:167], v[200:203], v[78:81]
	v_mfma_f32_16x16x32_bf16 v[70:73], v[160:163], v[204:207], v[70:73]
	v_mfma_f32_16x16x32_bf16 v[70:73], v[164:167], v[208:211], v[70:73]
	v_mfma_f32_16x16x32_bf16 v[106:109], v[168:171], v[176:179], v[106:109]
	v_mfma_f32_16x16x32_bf16 v[106:109], v[172:175], v[180:183], v[106:109]
	v_mfma_f32_16x16x32_bf16 v[90:93], v[168:171], v[184:187], v[90:93]
	v_mfma_f32_16x16x32_bf16 v[90:93], v[172:175], v[188:191], v[90:93]
	v_mfma_f32_16x16x32_bf16 v[74:77], v[168:171], v[192:195], v[74:77]
	v_mfma_f32_16x16x32_bf16 v[74:77], v[172:175], v[200:203], v[74:77]
	v_mfma_f32_16x16x32_bf16 v[66:69], v[168:171], v[204:207], v[66:69]
	v_mfma_f32_16x16x32_bf16 v[66:69], v[172:175], v[208:211], v[66:69]
	s_barrier
	s_add_u32 s98, s34, 0x80
	s_addc_u32 s99, s35, 0
	s_add_i32 s40, s54, s9
	s_mov_b32 m0, s40
	ds_read_b128 v[176:179], v143 offset:49152
	ds_read_b128 v[180:183], v143 offset:50176
	ds_read_b128 v[184:187], v143 offset:51200
	ds_read_b128 v[188:191], v143 offset:52224
	ds_read_b128 v[192:195], v143 offset:53248
	ds_read_b128 v[200:203], v143 offset:54272
	ds_read_b128 v[204:207], v143 offset:55296
	ds_read_b128 v[208:211], v143 offset:56320
	global_load_lds_dwordx4 v0, s[98:99]
	s_add_i32 m0, s40, 0x2000
	s_add_u32 s34, s34, 0x100080
	s_addc_u32 s35, s35, 0
	s_add_i32 s40, s55, s9
	global_load_lds_dwordx4 v130, s[98:99]
	s_mov_b32 m0, s40
	s_nop 0
	global_load_lds_dwordx4 v0, s[34:35]
	s_add_i32 m0, s40, 0x2000
	s_nop 0
	global_load_lds_dwordx4 v130, s[34:35]
	s_waitcnt vmcnt(6)
	s_waitcnt lgkmcnt(0)
	s_barrier
	s_waitcnt lgkmcnt(0)
	v_mfma_f32_16x16x32_bf16 v[62:65], v[144:147], v[176:179], v[62:65]
	v_mfma_f32_16x16x32_bf16 v[62:65], v[148:151], v[180:183], v[62:65]
	v_mfma_f32_16x16x32_bf16 v[54:57], v[144:147], v[184:187], v[54:57]
	v_mfma_f32_16x16x32_bf16 v[54:57], v[148:151], v[188:191], v[54:57]
	v_mfma_f32_16x16x32_bf16 v[38:41], v[144:147], v[192:195], v[38:41]
	v_mfma_f32_16x16x32_bf16 v[38:41], v[148:151], v[200:203], v[38:41]
	v_mfma_f32_16x16x32_bf16 v[22:25], v[144:147], v[204:207], v[22:25]
	v_mfma_f32_16x16x32_bf16 v[22:25], v[148:151], v[208:211], v[22:25]
	v_mfma_f32_16x16x32_bf16 v[58:61], v[152:155], v[176:179], v[58:61]
	v_mfma_f32_16x16x32_bf16 v[58:61], v[156:159], v[180:183], v[58:61]
	v_mfma_f32_16x16x32_bf16 v[50:53], v[152:155], v[184:187], v[50:53]
	v_mfma_f32_16x16x32_bf16 v[50:53], v[156:159], v[188:191], v[50:53]
	s_add_i32 s53, s53, 2
	v_mfma_f32_16x16x32_bf16 v[34:37], v[152:155], v[192:195], v[34:37]
	v_mfma_f32_16x16x32_bf16 v[34:37], v[156:159], v[200:203], v[34:37]
	s_add_u32 s30, s30, 0x100
	s_addc_u32 s31, s31, 0
	v_mfma_f32_16x16x32_bf16 v[18:21], v[152:155], v[204:207], v[18:21]
	v_mfma_f32_16x16x32_bf16 v[18:21], v[156:159], v[208:211], v[18:21]
	s_add_u32 s51, s51, 0x100
	s_addc_u32 s52, s52, 0
	v_mfma_f32_16x16x32_bf16 v[46:49], v[160:163], v[176:179], v[46:49]
	v_mfma_f32_16x16x32_bf16 v[46:49], v[164:167], v[180:183], v[46:49]
	s_add_u32 s98, s30, 0xfff00000
	s_addc_u32 s99, s31, -1
	v_mfma_f32_16x16x32_bf16 v[30:33], v[160:163], v[184:187], v[30:33]
	v_mfma_f32_16x16x32_bf16 v[30:33], v[164:167], v[188:191], v[30:33]
	s_add_u32 s34, s30, 0xfff00080
	s_addc_u32 s35, s31, -1
	v_mfma_f32_16x16x32_bf16 v[14:17], v[160:163], v[192:195], v[14:17]
	v_mfma_f32_16x16x32_bf16 v[14:17], v[164:167], v[200:203], v[14:17]
	s_add_i32 s54, 0, 0x10000
	v_mfma_f32_16x16x32_bf16 v[6:9], v[160:163], v[204:207], v[6:9]
	v_mfma_f32_16x16x32_bf16 v[6:9], v[164:167], v[208:211], v[6:9]
	s_cmp_eq_u32 s53, 60
	s_cselect_b32 s41, s25, s35
	s_cselect_b32 s40, s49, s34
	s_cselect_b32 s35, s23, s52
	s_cselect_b32 s34, s50, s51
	v_mfma_f32_16x16x32_bf16 v[42:45], v[168:171], v[176:179], v[42:45]
	v_mfma_f32_16x16x32_bf16 v[42:45], v[172:175], v[180:183], v[42:45]
	s_add_i32 s56, 0, 0x14000
	v_mfma_f32_16x16x32_bf16 v[26:29], v[168:171], v[184:187], v[26:29]
	v_mfma_f32_16x16x32_bf16 v[26:29], v[172:175], v[188:191], v[26:29]
	s_cmp_gt_u32 s53, 61
	v_mfma_f32_16x16x32_bf16 v[10:13], v[168:171], v[192:195], v[10:13]
	v_mfma_f32_16x16x32_bf16 v[10:13], v[172:175], v[200:203], v[10:13]
	v_mfma_f32_16x16x32_bf16 v[2:5], v[168:171], v[204:207], v[2:5]
	v_mfma_f32_16x16x32_bf16 v[2:5], v[172:175], v[208:211], v[2:5]
	s_barrier
	s_cbranch_scc0 .Lkb_801
	s_and_b64 vcc, exec, s[20:21]
	s_cbranch_vccz .LBB0_804
	s_barrier
